# k13 + every wave touches the 64 KB of code after the GEMM1 loop entry two iterations before each unit ends, so the epilogue instruction fetches hit L2
# speedup vs baseline: 1.0349x; 1.0136x over previous
.LBB0_241:
	s_ashr_i32 s75, s74, 31
	s_lshl_b64 s[22:23], s[74:75], 19
	s_add_u32 s68, s10, s22
	s_addc_u32 s69, s11, s23
	s_and_b64 s[22:23], s[36:37], exec
	s_cselect_b32 s22, s69, s1
	s_cselect_b32 s23, s68, s0
	s_ashr_i32 s7, s6, 31
	s_lshl_b64 s[38:39], s[6:7], 19
	s_add_u32 s80, s89, s38
	s_addc_u32 s81, s91, s39
	s_and_b64 s[36:37], s[36:37], exec
	s_cselect_b32 s7, s81, s5
	s_cselect_b32 s25, s80, s4
	s_add_u32 s0, s0, 0x40080
	s_addc_u32 s1, s1, 0
	s_add_u32 s38, s4, 0x100
	v_mov_b32_e32 v0, 0
	s_addc_u32 s39, s5, 0
	s_mov_b32 s75, -2
	s_waitcnt lgkmcnt(0)
	v_mov_b32_e32 v1, v0
	v_mov_b32_e32 v2, v0
	v_mov_b32_e32 v3, v0
	v_mov_b32_e32 v4, v0
	v_mov_b32_e32 v5, v0
	v_mov_b32_e32 v6, v0
	v_mov_b32_e32 v7, v0
	v_mov_b32_e32 v16, v0
	v_mov_b32_e32 v17, v0
	v_mov_b32_e32 v18, v0
	v_mov_b32_e32 v19, v0
	v_mov_b32_e32 v20, v0
	v_mov_b32_e32 v21, v0
	v_mov_b32_e32 v22, v0
	v_mov_b32_e32 v23, v0
	v_mov_b32_e32 v32, v0
	v_mov_b32_e32 v33, v0
	v_mov_b32_e32 v34, v0
	v_mov_b32_e32 v35, v0
	v_mov_b32_e32 v36, v0
	v_mov_b32_e32 v37, v0
	v_mov_b32_e32 v38, v0
	v_mov_b32_e32 v39, v0
	v_mov_b32_e32 v48, v0
	v_mov_b32_e32 v49, v0
	v_mov_b32_e32 v50, v0
	v_mov_b32_e32 v51, v0
	v_mov_b32_e32 v52, v0
	v_mov_b32_e32 v53, v0
	v_mov_b32_e32 v54, v0
	v_mov_b32_e32 v55, v0
	v_mov_b32_e32 v8, v0
	v_mov_b32_e32 v9, v0
	v_mov_b32_e32 v10, v0
	v_mov_b32_e32 v11, v0
	v_mov_b32_e32 v12, v0
	v_mov_b32_e32 v13, v0
	v_mov_b32_e32 v14, v0
	v_mov_b32_e32 v15, v0
	v_mov_b32_e32 v24, v0
	v_mov_b32_e32 v25, v0
	v_mov_b32_e32 v26, v0
	v_mov_b32_e32 v27, v0
	v_mov_b32_e32 v28, v0
	v_mov_b32_e32 v29, v0
	v_mov_b32_e32 v30, v0
	v_mov_b32_e32 v31, v0
	v_mov_b32_e32 v40, v0
	v_mov_b32_e32 v41, v0
	v_mov_b32_e32 v42, v0
	v_mov_b32_e32 v43, v0
	v_mov_b32_e32 v44, v0
	v_mov_b32_e32 v45, v0
	v_mov_b32_e32 v46, v0
	v_mov_b32_e32 v47, v0
	v_mov_b32_e32 v56, v0
	v_mov_b32_e32 v57, v0
	v_mov_b32_e32 v58, v0
	v_mov_b32_e32 v59, v0
	v_mov_b32_e32 v60, v0
	v_mov_b32_e32 v61, v0
	v_mov_b32_e32 v62, v0
	v_mov_b32_e32 v63, v0
	v_mov_b32_e32 v64, v0
	v_mov_b32_e32 v65, v0
	v_mov_b32_e32 v66, v0
	v_mov_b32_e32 v67, v0
	v_mov_b32_e32 v68, v0
	v_mov_b32_e32 v69, v0
	v_mov_b32_e32 v70, v0
	v_mov_b32_e32 v71, v0
	v_mov_b32_e32 v80, v0
	v_mov_b32_e32 v81, v0
	v_mov_b32_e32 v82, v0
	v_mov_b32_e32 v83, v0
	v_mov_b32_e32 v84, v0
	v_mov_b32_e32 v85, v0
	v_mov_b32_e32 v86, v0
	v_mov_b32_e32 v87, v0
	v_mov_b32_e32 v96, v0
	v_mov_b32_e32 v97, v0
	v_mov_b32_e32 v98, v0
	v_mov_b32_e32 v99, v0
	v_mov_b32_e32 v100, v0
	v_mov_b32_e32 v101, v0
	v_mov_b32_e32 v102, v0
	v_mov_b32_e32 v103, v0
	v_mov_b32_e32 v112, v0
	v_mov_b32_e32 v113, v0
	v_mov_b32_e32 v114, v0
	v_mov_b32_e32 v115, v0
	v_mov_b32_e32 v116, v0
	v_mov_b32_e32 v117, v0
	v_mov_b32_e32 v118, v0
	v_mov_b32_e32 v119, v0
	v_mov_b32_e32 v72, v0
	v_mov_b32_e32 v73, v0
	v_mov_b32_e32 v74, v0
	v_mov_b32_e32 v75, v0
	v_mov_b32_e32 v76, v0
	v_mov_b32_e32 v77, v0
	v_mov_b32_e32 v78, v0
	v_mov_b32_e32 v79, v0
	v_mov_b32_e32 v88, v0
	v_mov_b32_e32 v89, v0
	v_mov_b32_e32 v90, v0
	v_mov_b32_e32 v91, v0
	v_mov_b32_e32 v92, v0
	v_mov_b32_e32 v93, v0
	v_mov_b32_e32 v94, v0
	v_mov_b32_e32 v95, v0
	v_mov_b32_e32 v104, v0
	v_mov_b32_e32 v105, v0
	v_mov_b32_e32 v106, v0
	v_mov_b32_e32 v107, v0
	v_mov_b32_e32 v108, v0
	v_mov_b32_e32 v109, v0
	v_mov_b32_e32 v110, v0
	v_mov_b32_e32 v111, v0
	v_mov_b32_e32 v120, v0
	v_mov_b32_e32 v121, v0
	v_mov_b32_e32 v122, v0
	v_mov_b32_e32 v123, v0
	v_mov_b32_e32 v124, v0
	v_mov_b32_e32 v125, v0
	v_mov_b32_e32 v126, v0
	v_mov_b32_e32 v127, v0
	s_getpc_b64 s[98:99]
	v_lshlrev_b32_e32 v246, 7, v202
	v_mov_b32_e32 v247, 0
	v_lshl_add_u64 v[246:247], v[246:247], 0, s[98:99]
.LBB0_242:
	s_add_u32 s4, s0, 0xfffc0080
	s_addc_u32 s5, s1, -1
	s_add_i32 vcc_lo, 0, 0x10000
	v_add_u32_e32 v128, vcc_lo, v162
	ds_read_b128 v[142:145], v128
	ds_read_b128 v[146:149], v128 offset:1024
	ds_read_b128 v[150:153], v128 offset:2048
	ds_read_b128 v[154:157], v128 offset:3072
	s_cmp_eq_u32 s75, 12
	s_cselect_b32 s37, s22, s5
	s_cselect_b32 s36, s23, s4
	s_cselect_b32 s5, s7, s39
	s_cselect_b32 s4, s25, s38
	v_lshl_add_u64 v[196:197], s[0:1], 0, v[138:139]
	s_add_i32 m0, s95, 0xc000
	ds_read_b128 v[164:167], v163
	ds_read_b128 v[168:171], v163 offset:1024
	ds_read_b128 v[172:175], v163 offset:2048
	ds_read_b128 v[176:179], v163 offset:3072
	ds_read_b128 v[180:183], v163 offset:4096
	ds_read_b128 v[184:187], v163 offset:5120
	ds_read_b128 v[188:191], v163 offset:6144
	ds_read_b128 v[192:195], v163 offset:7168
	global_load_lds_dwordx4 v[196:197], off
	v_lshl_add_u64 v[196:197], s[0:1], 0, v[140:141]
	s_add_i32 m0, s95, 0xe000
	s_nop 0
	global_load_lds_dwordx4 v[196:197], off
	s_cmp_eq_u32 s75, 10
	s_cbranch_scc0 .Lct_skip
	global_load_dword v248, v[246:247], off
.Lct_skip:
	s_waitcnt lgkmcnt(8)
	s_barrier
	s_waitcnt lgkmcnt(0)
	s_setprio 1
	s_waitcnt lgkmcnt(0)
	v_mfma_f32_16x16x32_bf16 v[124:127], v[142:145], v[164:167], v[124:127]
	v_mfma_f32_16x16x32_bf16 v[120:123], v[150:153], v[164:167], v[120:123]
	v_mfma_f32_16x16x32_bf16 v[108:111], v[142:145], v[172:175], v[108:111]
	v_mfma_f32_16x16x32_bf16 v[104:107], v[150:153], v[172:175], v[104:107]
	v_mfma_f32_16x16x32_bf16 v[92:95], v[142:145], v[180:183], v[92:95]
	v_mfma_f32_16x16x32_bf16 v[88:91], v[150:153], v[180:183], v[88:91]
	v_mfma_f32_16x16x32_bf16 v[76:79], v[142:145], v[188:191], v[76:79]
	v_mfma_f32_16x16x32_bf16 v[72:75], v[150:153], v[188:191], v[72:75]
	v_mfma_f32_16x16x32_bf16 v[124:127], v[146:149], v[168:171], v[124:127]
	v_mfma_f32_16x16x32_bf16 v[120:123], v[154:157], v[168:171], v[120:123]
	v_mfma_f32_16x16x32_bf16 v[108:111], v[146:149], v[176:179], v[108:111]
	v_mfma_f32_16x16x32_bf16 v[104:107], v[154:157], v[176:179], v[104:107]
	v_mfma_f32_16x16x32_bf16 v[92:95], v[146:149], v[184:187], v[92:95]
	v_mfma_f32_16x16x32_bf16 v[88:91], v[154:157], v[184:187], v[88:91]
	v_mfma_f32_16x16x32_bf16 v[76:79], v[146:149], v[192:195], v[76:79]
	v_mfma_f32_16x16x32_bf16 v[72:75], v[154:157], v[192:195], v[72:75]
	s_setprio 0
	s_barrier
	s_add_i32 s26, 0, 0x14000
	s_add_i32 s27, vcc_lo, s87
	v_add_u32_e32 v128, s26, v162
	v_lshl_add_u64 v[200:201], s[4:5], 0, v[132:133]
	s_mov_b32 m0, s27
	ds_read_b128 v[196:199], v128
	ds_read_b128 v[210:213], v128 offset:1024
	ds_read_b128 v[214:217], v128 offset:2048
	ds_read_b128 v[218:221], v128 offset:3072
	global_load_lds_dwordx4 v[200:201], off
	v_lshl_add_u64 v[222:223], s[4:5], 0, v[136:137]
	s_add_i32 m0, s27, 0x2000
	s_nop 0
	global_load_lds_dwordx4 v[222:223], off
	s_barrier
	s_waitcnt lgkmcnt(0)
	s_setprio 1
	s_waitcnt lgkmcnt(0)
	v_mfma_f32_16x16x32_bf16 v[116:119], v[196:199], v[164:167], v[116:119]
	v_mfma_f32_16x16x32_bf16 v[112:115], v[214:217], v[164:167], v[112:115]
	v_mfma_f32_16x16x32_bf16 v[100:103], v[196:199], v[172:175], v[100:103]
	v_mfma_f32_16x16x32_bf16 v[96:99], v[214:217], v[172:175], v[96:99]
	v_mfma_f32_16x16x32_bf16 v[84:87], v[196:199], v[180:183], v[84:87]
	v_mfma_f32_16x16x32_bf16 v[80:83], v[214:217], v[180:183], v[80:83]
	v_mfma_f32_16x16x32_bf16 v[68:71], v[196:199], v[188:191], v[68:71]
	v_mfma_f32_16x16x32_bf16 v[64:67], v[214:217], v[188:191], v[64:67]
	v_mfma_f32_16x16x32_bf16 v[116:119], v[210:213], v[168:171], v[116:119]
	v_mfma_f32_16x16x32_bf16 v[112:115], v[218:221], v[168:171], v[112:115]
	v_mfma_f32_16x16x32_bf16 v[100:103], v[210:213], v[176:179], v[100:103]
	v_mfma_f32_16x16x32_bf16 v[96:99], v[218:221], v[176:179], v[96:99]
	v_mfma_f32_16x16x32_bf16 v[84:87], v[210:213], v[184:187], v[84:87]
	v_mfma_f32_16x16x32_bf16 v[80:83], v[218:221], v[184:187], v[80:83]
	v_mfma_f32_16x16x32_bf16 v[68:71], v[210:213], v[192:195], v[68:71]
	v_mfma_f32_16x16x32_bf16 v[64:67], v[218:221], v[192:195], v[64:67]
	s_setprio 0
	s_mov_b32 m0, s95
	v_lshl_add_u64 v[224:225], s[36:37], 0, v[130:131]
	s_barrier
	ds_read_b128 v[164:167], v163 offset:16384
	ds_read_b128 v[168:171], v163 offset:17408
	ds_read_b128 v[172:175], v163 offset:18432
	ds_read_b128 v[176:179], v163 offset:19456
	ds_read_b128 v[180:183], v163 offset:20480
	ds_read_b128 v[184:187], v163 offset:21504
	ds_read_b128 v[188:191], v163 offset:22528
	ds_read_b128 v[192:195], v163 offset:23552
	global_load_lds_dwordx4 v[224:225], off
	v_lshl_add_u64 v[226:227], s[36:37], 0, v[134:135]
	s_mov_b32 m0, s97
	s_nop 0
	global_load_lds_dwordx4 v[226:227], off
	s_barrier
	s_waitcnt lgkmcnt(0)
	s_setprio 1
	s_waitcnt lgkmcnt(0)
	v_mfma_f32_16x16x32_bf16 v[60:63], v[142:145], v[164:167], v[60:63]
	v_mfma_f32_16x16x32_bf16 v[56:59], v[150:153], v[164:167], v[56:59]
	v_mfma_f32_16x16x32_bf16 v[44:47], v[142:145], v[172:175], v[44:47]
	v_mfma_f32_16x16x32_bf16 v[40:43], v[150:153], v[172:175], v[40:43]
	v_mfma_f32_16x16x32_bf16 v[28:31], v[142:145], v[180:183], v[28:31]
	v_mfma_f32_16x16x32_bf16 v[24:27], v[150:153], v[180:183], v[24:27]
	v_mfma_f32_16x16x32_bf16 v[12:15], v[142:145], v[188:191], v[12:15]
	v_mfma_f32_16x16x32_bf16 v[8:11], v[150:153], v[188:191], v[8:11]
	v_mfma_f32_16x16x32_bf16 v[60:63], v[146:149], v[168:171], v[60:63]
	v_mfma_f32_16x16x32_bf16 v[56:59], v[154:157], v[168:171], v[56:59]
	v_mfma_f32_16x16x32_bf16 v[44:47], v[146:149], v[176:179], v[44:47]
	v_mfma_f32_16x16x32_bf16 v[40:43], v[154:157], v[176:179], v[40:43]
	v_mfma_f32_16x16x32_bf16 v[28:31], v[146:149], v[184:187], v[28:31]
	v_mfma_f32_16x16x32_bf16 v[24:27], v[154:157], v[184:187], v[24:27]
	v_mfma_f32_16x16x32_bf16 v[12:15], v[146:149], v[192:195], v[12:15]
	v_mfma_f32_16x16x32_bf16 v[8:11], v[154:157], v[192:195], v[8:11]
	s_setprio 0
	s_barrier
	s_add_u32 vcc_lo, s4, 0x40000
	s_addc_u32 vcc_hi, s5, 0
	s_add_i32 s26, s26, s87
	v_lshl_add_u64 v[142:143], vcc, 0, v[132:133]
	s_mov_b32 m0, s26
	s_nop 0
	global_load_lds_dwordx4 v[142:143], off
	v_lshl_add_u64 v[142:143], vcc, 0, v[136:137]
	s_add_i32 m0, s26, 0x2000
	s_nop 0
	global_load_lds_dwordx4 v[142:143], off
	s_waitcnt vmcnt(6)
	s_barrier
	s_setprio 1
	v_mfma_f32_16x16x32_bf16 v[52:55], v[196:199], v[164:167], v[52:55]
	v_mfma_f32_16x16x32_bf16 v[48:51], v[214:217], v[164:167], v[48:51]
	v_mfma_f32_16x16x32_bf16 v[36:39], v[196:199], v[172:175], v[36:39]
	v_mfma_f32_16x16x32_bf16 v[32:35], v[214:217], v[172:175], v[32:35]
	v_mfma_f32_16x16x32_bf16 v[20:23], v[196:199], v[180:183], v[20:23]
	v_mfma_f32_16x16x32_bf16 v[16:19], v[214:217], v[180:183], v[16:19]
	v_mfma_f32_16x16x32_bf16 v[4:7], v[196:199], v[188:191], v[4:7]
	v_mfma_f32_16x16x32_bf16 v[0:3], v[214:217], v[188:191], v[0:3]
	v_mfma_f32_16x16x32_bf16 v[52:55], v[210:213], v[168:171], v[52:55]
	v_mfma_f32_16x16x32_bf16 v[48:51], v[218:221], v[168:171], v[48:51]
	v_mfma_f32_16x16x32_bf16 v[36:39], v[210:213], v[176:179], v[36:39]
	v_mfma_f32_16x16x32_bf16 v[32:35], v[218:221], v[176:179], v[32:35]
	v_mfma_f32_16x16x32_bf16 v[20:23], v[210:213], v[184:187], v[20:23]
	v_mfma_f32_16x16x32_bf16 v[16:19], v[218:221], v[184:187], v[16:19]
	v_mfma_f32_16x16x32_bf16 v[4:7], v[210:213], v[192:195], v[4:7]
	v_mfma_f32_16x16x32_bf16 v[0:3], v[218:221], v[192:195], v[0:3]
	s_setprio 0
	s_add_i32 s26, 0, 0x18000
	v_add_u32_e32 v128, s26, v162
	s_barrier
	ds_read_b128 v[142:145], v128
	ds_read_b128 v[146:149], v128 offset:1024
	ds_read_b128 v[150:153], v128 offset:2048
	ds_read_b128 v[154:157], v128 offset:3072
	s_add_u32 s36, s36, 0x40000
	s_addc_u32 s37, s37, 0
	s_mov_b32 m0, s33
	v_lshl_add_u64 v[196:197], s[36:37], 0, v[130:131]
	ds_read_b128 v[164:167], v163 offset:32768
	ds_read_b128 v[168:171], v163 offset:33792
	ds_read_b128 v[172:175], v163 offset:34816
	ds_read_b128 v[176:179], v163 offset:35840
	ds_read_b128 v[180:183], v163 offset:36864
	ds_read_b128 v[184:187], v163 offset:37888
	ds_read_b128 v[188:191], v163 offset:38912
	ds_read_b128 v[192:195], v163 offset:39936
	global_load_lds_dwordx4 v[196:197], off
	v_lshl_add_u64 v[196:197], s[36:37], 0, v[134:135]
	s_mov_b32 m0, s93
	s_nop 0
	global_load_lds_dwordx4 v[196:197], off
	s_waitcnt lgkmcnt(8)
	s_barrier
	s_waitcnt lgkmcnt(0)
	s_setprio 1
	s_waitcnt lgkmcnt(0)
	v_mfma_f32_16x16x32_bf16 v[124:127], v[142:145], v[164:167], v[124:127]
	v_mfma_f32_16x16x32_bf16 v[120:123], v[150:153], v[164:167], v[120:123]
	v_mfma_f32_16x16x32_bf16 v[108:111], v[142:145], v[172:175], v[108:111]
	v_mfma_f32_16x16x32_bf16 v[104:107], v[150:153], v[172:175], v[104:107]
	v_mfma_f32_16x16x32_bf16 v[92:95], v[142:145], v[180:183], v[92:95]
	v_mfma_f32_16x16x32_bf16 v[88:91], v[150:153], v[180:183], v[88:91]
	v_mfma_f32_16x16x32_bf16 v[76:79], v[142:145], v[188:191], v[76:79]
	v_mfma_f32_16x16x32_bf16 v[72:75], v[150:153], v[188:191], v[72:75]
	v_mfma_f32_16x16x32_bf16 v[124:127], v[146:149], v[168:171], v[124:127]
	v_mfma_f32_16x16x32_bf16 v[120:123], v[154:157], v[168:171], v[120:123]
	v_mfma_f32_16x16x32_bf16 v[108:111], v[146:149], v[176:179], v[108:111]
	v_mfma_f32_16x16x32_bf16 v[104:107], v[154:157], v[176:179], v[104:107]
	v_mfma_f32_16x16x32_bf16 v[92:95], v[146:149], v[184:187], v[92:95]
	v_mfma_f32_16x16x32_bf16 v[88:91], v[154:157], v[184:187], v[88:91]
	v_mfma_f32_16x16x32_bf16 v[76:79], v[146:149], v[192:195], v[76:79]
	v_mfma_f32_16x16x32_bf16 v[72:75], v[154:157], v[192:195], v[72:75]
	s_setprio 0
	s_barrier
	s_add_i32 s27, 0, 0x1c000
	s_add_i32 s26, s26, s87
	v_add_u32_e32 v128, s27, v162
	v_lshl_add_u64 v[200:201], v[200:201], 0, s[82:83]
	s_mov_b32 m0, s26
	ds_read_b128 v[196:199], v128
	ds_read_b128 v[210:213], v128 offset:1024
	ds_read_b128 v[214:217], v128 offset:2048
	ds_read_b128 v[218:221], v128 offset:3072
	global_load_lds_dwordx4 v[200:201], off
	v_lshl_add_u64 v[200:201], v[222:223], 0, s[82:83]
	s_add_i32 m0, s26, 0x2000
	s_nop 0
	global_load_lds_dwordx4 v[200:201], off
	s_barrier
	s_waitcnt lgkmcnt(0)
	s_setprio 1
	s_waitcnt lgkmcnt(0)
	v_mfma_f32_16x16x32_bf16 v[116:119], v[196:199], v[164:167], v[116:119]
	v_mfma_f32_16x16x32_bf16 v[112:115], v[214:217], v[164:167], v[112:115]
	v_mfma_f32_16x16x32_bf16 v[100:103], v[196:199], v[172:175], v[100:103]
	v_mfma_f32_16x16x32_bf16 v[96:99], v[214:217], v[172:175], v[96:99]
	v_mfma_f32_16x16x32_bf16 v[84:87], v[196:199], v[180:183], v[84:87]
	v_mfma_f32_16x16x32_bf16 v[80:83], v[214:217], v[180:183], v[80:83]
	v_mfma_f32_16x16x32_bf16 v[68:71], v[196:199], v[188:191], v[68:71]
	v_mfma_f32_16x16x32_bf16 v[64:67], v[214:217], v[188:191], v[64:67]
	v_mfma_f32_16x16x32_bf16 v[116:119], v[210:213], v[168:171], v[116:119]
	v_mfma_f32_16x16x32_bf16 v[112:115], v[218:221], v[168:171], v[112:115]
	v_mfma_f32_16x16x32_bf16 v[100:103], v[210:213], v[176:179], v[100:103]
	v_mfma_f32_16x16x32_bf16 v[96:99], v[218:221], v[176:179], v[96:99]
	v_mfma_f32_16x16x32_bf16 v[84:87], v[210:213], v[184:187], v[84:87]
	v_mfma_f32_16x16x32_bf16 v[80:83], v[218:221], v[184:187], v[80:83]
	v_mfma_f32_16x16x32_bf16 v[68:71], v[210:213], v[192:195], v[68:71]
	v_mfma_f32_16x16x32_bf16 v[64:67], v[218:221], v[192:195], v[64:67]
	s_setprio 0
	s_mov_b32 m0, s12
	v_lshl_add_u64 v[200:201], v[224:225], 0, s[82:83]
	s_barrier
	ds_read_b128 v[164:167], v163 offset:49152
	ds_read_b128 v[168:171], v163 offset:50176
	ds_read_b128 v[172:175], v163 offset:51200
	ds_read_b128 v[176:179], v163 offset:52224
	ds_read_b128 v[180:183], v163 offset:53248
	ds_read_b128 v[184:187], v163 offset:54272
	ds_read_b128 v[188:191], v163 offset:55296
	ds_read_b128 v[192:195], v163 offset:56320
	global_load_lds_dwordx4 v[200:201], off
	v_lshl_add_u64 v[200:201], v[226:227], 0, s[82:83]
	s_mov_b32 m0, s13
	s_nop 0
	global_load_lds_dwordx4 v[200:201], off
	s_barrier
	s_waitcnt lgkmcnt(0)
	s_setprio 1
	s_waitcnt lgkmcnt(0)
	v_mfma_f32_16x16x32_bf16 v[60:63], v[142:145], v[164:167], v[60:63]
	v_mfma_f32_16x16x32_bf16 v[56:59], v[150:153], v[164:167], v[56:59]
	v_mfma_f32_16x16x32_bf16 v[44:47], v[142:145], v[172:175], v[44:47]
	v_mfma_f32_16x16x32_bf16 v[40:43], v[150:153], v[172:175], v[40:43]
	v_mfma_f32_16x16x32_bf16 v[28:31], v[142:145], v[180:183], v[28:31]
	v_mfma_f32_16x16x32_bf16 v[24:27], v[150:153], v[180:183], v[24:27]
	v_mfma_f32_16x16x32_bf16 v[12:15], v[142:145], v[188:191], v[12:15]
	v_mfma_f32_16x16x32_bf16 v[8:11], v[150:153], v[188:191], v[8:11]
	v_mfma_f32_16x16x32_bf16 v[60:63], v[146:149], v[168:171], v[60:63]
	v_mfma_f32_16x16x32_bf16 v[56:59], v[154:157], v[168:171], v[56:59]
	v_mfma_f32_16x16x32_bf16 v[44:47], v[146:149], v[176:179], v[44:47]
	v_mfma_f32_16x16x32_bf16 v[40:43], v[154:157], v[176:179], v[40:43]
	v_mfma_f32_16x16x32_bf16 v[28:31], v[146:149], v[184:187], v[28:31]
	v_mfma_f32_16x16x32_bf16 v[24:27], v[154:157], v[184:187], v[24:27]
	v_mfma_f32_16x16x32_bf16 v[12:15], v[146:149], v[192:195], v[12:15]
	v_mfma_f32_16x16x32_bf16 v[8:11], v[154:157], v[192:195], v[8:11]
	s_setprio 0
	s_barrier
	s_add_u32 s4, s4, 0x40080
	s_addc_u32 s5, s5, 0
	s_add_i32 s26, s27, s87
	v_lshl_add_u64 v[142:143], s[4:5], 0, v[132:133]
	s_mov_b32 m0, s26
	s_nop 0
	global_load_lds_dwordx4 v[142:143], off
	v_lshl_add_u64 v[142:143], s[4:5], 0, v[136:137]
	s_add_i32 m0, s26, 0x2000
	s_nop 0
	global_load_lds_dwordx4 v[142:143], off
	s_waitcnt vmcnt(6)
	s_barrier
	s_setprio 1
	v_mfma_f32_16x16x32_bf16 v[52:55], v[196:199], v[164:167], v[52:55]
	v_mfma_f32_16x16x32_bf16 v[48:51], v[214:217], v[164:167], v[48:51]
	v_mfma_f32_16x16x32_bf16 v[36:39], v[196:199], v[172:175], v[36:39]
	v_mfma_f32_16x16x32_bf16 v[32:35], v[214:217], v[172:175], v[32:35]
	v_mfma_f32_16x16x32_bf16 v[20:23], v[196:199], v[180:183], v[20:23]
	v_mfma_f32_16x16x32_bf16 v[16:19], v[214:217], v[180:183], v[16:19]
	v_mfma_f32_16x16x32_bf16 v[4:7], v[196:199], v[188:191], v[4:7]
	v_mfma_f32_16x16x32_bf16 v[0:3], v[214:217], v[188:191], v[0:3]
	v_mfma_f32_16x16x32_bf16 v[52:55], v[210:213], v[168:171], v[52:55]
	v_mfma_f32_16x16x32_bf16 v[48:51], v[218:221], v[168:171], v[48:51]
	v_mfma_f32_16x16x32_bf16 v[36:39], v[210:213], v[176:179], v[36:39]
	v_mfma_f32_16x16x32_bf16 v[32:35], v[218:221], v[176:179], v[32:35]
	v_mfma_f32_16x16x32_bf16 v[20:23], v[210:213], v[184:187], v[20:23]
	v_mfma_f32_16x16x32_bf16 v[16:19], v[218:221], v[184:187], v[16:19]
	v_mfma_f32_16x16x32_bf16 v[4:7], v[210:213], v[192:195], v[4:7]
	v_mfma_f32_16x16x32_bf16 v[0:3], v[218:221], v[192:195], v[0:3]
	s_setprio 0
	s_add_i32 s75, s75, 2
	s_add_u32 s0, s0, 0x100
	s_addc_u32 s1, s1, 0
	s_add_u32 s38, s38, 0x100
	s_addc_u32 s39, s39, 0
	s_cmp_gt_u32 s75, 13
	s_barrier
	s_cbranch_scc0 .LBB0_242
	s_cmpk_gt_u32 s85, 0xff
	s_cbranch_scc1 .Lus1
	s_barrier

	.amdhsa_kernel _Z10fwd_kernel4Args
		.amdhsa_group_segment_fixed_size 0
		.amdhsa_private_segment_fixed_size 0
		.amdhsa_kernarg_size 432
		.amdhsa_user_sgpr_count 2
		.amdhsa_user_sgpr_dispatch_ptr 0
		.amdhsa_user_sgpr_queue_ptr 0
		.amdhsa_user_sgpr_kernarg_segment_ptr 1
		.amdhsa_user_sgpr_dispatch_id 0
		.amdhsa_user_sgpr_kernarg_preload_length 0
		.amdhsa_user_sgpr_kernarg_preload_offset 0
		.amdhsa_user_sgpr_private_segment_size 0
		.amdhsa_uses_dynamic_stack 0
		.amdhsa_enable_private_segment 0
		.amdhsa_system_sgpr_workgroup_id_x 1
		.amdhsa_system_sgpr_workgroup_id_y 0
		.amdhsa_system_sgpr_workgroup_id_z 0
		.amdhsa_system_sgpr_workgroup_info 0
		.amdhsa_system_vgpr_workitem_id 2
		.amdhsa_next_free_vgpr 249
		.amdhsa_next_free_sgpr 102
		.amdhsa_accum_offset 252
		.amdhsa_reserve_vcc 1
		.amdhsa_float_round_mode_32 0
		.amdhsa_float_round_mode_16_64 0
		.amdhsa_float_denorm_mode_32 3
		.amdhsa_float_denorm_mode_16_64 3
		.amdhsa_dx10_clamp 1
		.amdhsa_ieee_mode 1
		.amdhsa_fp16_overflow 0
		.amdhsa_tg_split 0
		.amdhsa_exception_fp_ieee_invalid_op 0
		.amdhsa_exception_fp_denorm_src 0
		.amdhsa_exception_fp_ieee_div_zero 0
		.amdhsa_exception_fp_ieee_overflow 0
		.amdhsa_exception_fp_ieee_underflow 0
		.amdhsa_exception_fp_ieee_inexact 0
		.amdhsa_exception_int_div_zero 0
	.end_amdhsa_kernel

amdhsa.kernels:
  - .agpr_count:     0
    .args:
      - .offset:         0
        .size:           176
        .value_kind:     by_value
      - .offset:         176
        .size:           4
        .value_kind:     hidden_block_count_x
      - .offset:         180
        .size:           4
        .value_kind:     hidden_block_count_y
      - .offset:         184
        .size:           4
        .value_kind:     hidden_block_count_z
      - .offset:         188
        .size:           2
        .value_kind:     hidden_group_size_x
      - .offset:         190
        .size:           2
        .value_kind:     hidden_group_size_y
      - .offset:         192
        .size:           2
        .value_kind:     hidden_group_size_z
      - .offset:         194
        .size:           2
        .value_kind:     hidden_remainder_x
      - .offset:         196
        .size:           2
        .value_kind:     hidden_remainder_y
      - .offset:         198
        .size:           2
        .value_kind:     hidden_remainder_z
      - .offset:         216
        .size:           8
        .value_kind:     hidden_global_offset_x
      - .offset:         224
        .size:           8
        .value_kind:     hidden_global_offset_y
      - .offset:         232
        .size:           8
        .value_kind:     hidden_global_offset_z
      - .offset:         240
        .size:           2
        .value_kind:     hidden_grid_dims
      - .offset:         264
        .size:           8
        .value_kind:     hidden_multigrid_sync_arg
      - .offset:         296
        .size:           4
        .value_kind:     hidden_dynamic_lds_size
    .group_segment_fixed_size: 0
    .kernarg_segment_align: 8
    .kernarg_segment_size: 432
    .language:       OpenCL C
    .language_version:
      - 2
      - 0
    .max_flat_workgroup_size: 512
    .name:           _Z10fwd_kernel4Args
    .private_segment_fixed_size: 0
    .sgpr_count:     108
    .sgpr_spill_count: 51
    .symbol:         _Z10fwd_kernel4Args.kd
    .uniform_work_group_size: 1
    .uses_dynamic_stack: false
    .vgpr_count:     249
    .vgpr_spill_count: 0
    .wavefront_size: 64
